# attention diagonal-tile bias block: 15 v_pk_add_f32 + 32 v_pk_fma_f32 split into scalar add / fmac pairs (packed f32 is slow beside the partner wave's MFMAs); stacked on stack35
# baseline (speedup 1.0000x reference)
; #define ATT_DIAG_BIAS(s0, s1) do { const float dqh_ = dq - (float)(4 * hi); _Pragma("unroll") for (int r = 0; r < 16; ++r) { const float c_ = (float)((r & 3) + 8 * (r >> 2)); \
;         s0[r] = __builtin_fmaf(-sl, __builtin_fabsf(dqh_ - c_), s0[r]); s1[r] = __builtin_fmaf(-sl, __builtin_fabsf(dqh_ - (c_ + 32.f)), s1[r]); } } while (0)
;     ...
;           if (diag) { ATT_DIAG_BIAS(sa0, sa1); ATT_DIAG_BIAS(sb0, sb1); }
.Latt_diag:
	s_lshl_b32 s34, s30, 6
	v_subrev_u32_e32 v128, s34, v171
	v_cvt_f32_i32_e32 v199, v128
	s_mov_b32 s34, 0xc2000000
	v_sub_f32_e32 v128, v199, v184
	s_mov_b32 s35, 0xc2040000
	v_add_f32_e32 v158, s34, v128
	v_add_f32_e32 v159, s35, v128
	s_mov_b32 s34, -2.0
	s_mov_b32 s35, 0xc0400000
	v_add_f32_e32 v160, s34, v128
	v_add_f32_e32 v161, s35, v128
	s_mov_b32 s34, 0xc2080000
	s_mov_b32 s35, 0xc20c0000
	v_add_f32_e32 v162, s34, v128
	v_add_f32_e32 v163, s35, v128
	s_mov_b32 s34, 0xc1000000
	s_mov_b32 s35, 0xc1100000
	v_add_f32_e32 v186, s34, v128
	v_add_f32_e32 v187, s35, v128
	s_mov_b32 s34, 0xc2200000
	s_mov_b32 s35, 0xc2240000
	v_add_f32_e32 v188, s34, v128
	v_add_f32_e32 v189, s35, v128
	s_mov_b32 s34, 0xc1200000
	s_mov_b32 s35, 0xc1300000
	v_add_f32_e32 v192, s34, v128
	v_add_f32_e32 v193, s35, v128
	s_mov_b32 s34, 0xc2280000
	s_mov_b32 s35, 0xc22c0000
	v_add_f32_e32 v194, s34, v128
	v_add_f32_e32 v195, s35, v128
	s_mov_b32 s34, 0xc1800000
	s_mov_b32 s35, 0xc1880000
	v_add_f32_e32 v200, s34, v128
	v_add_f32_e32 v201, s35, v128
	s_mov_b32 s34, 0xc2400000
	s_mov_b32 s35, 0xc2440000
	v_add_f32_e32 v202, s34, v128
	v_add_f32_e32 v203, s35, v128
	s_mov_b32 s34, 0xc1900000
	s_mov_b32 s35, 0xc1980000
	v_add_f32_e32 v204, s34, v128
	v_add_f32_e32 v205, s35, v128
	s_mov_b32 s34, 0xc2480000
	s_mov_b32 s35, 0xc24c0000
	v_add_f32_e32 v206, s34, v128
	v_add_f32_e32 v207, s35, v128
	s_mov_b32 s34, 0xc1c00000
	s_mov_b32 s35, 0xc1c80000
	v_add_f32_e32 v208, s34, v128
	v_add_f32_e32 v209, s35, v128
	s_mov_b32 s34, 0xc2600000
	s_mov_b32 s35, 0xc2640000
	v_add_f32_e32 v210, s34, v128
	v_add_f32_e32 v211, s35, v128
	s_mov_b32 s34, 0xc1d00000
	s_mov_b32 s35, 0xc1d80000
	v_add_f32_e32 v214, s34, v128
	v_add_f32_e32 v215, s35, v128
	s_mov_b32 s34, 0xc2680000
	s_mov_b32 s35, 0xc26c0000
	v_add_f32_e32 v155, -1.0, v128
	v_add_f32_e32 v222, s34, v128
	v_add_f32_e32 v223, s35, v128
	v_and_b32_e32 v159, 0x7fffffff, v159
	v_and_b32_e32 v158, 0x7fffffff, v158
	v_and_b32_e32 v163, 0x7fffffff, v163
	v_and_b32_e32 v162, 0x7fffffff, v162
	v_and_b32_e32 v187, 0x7fffffff, v187
	v_and_b32_e32 v186, 0x7fffffff, v186
	v_and_b32_e32 v189, 0x7fffffff, v189
	v_and_b32_e32 v188, 0x7fffffff, v188
	v_and_b32_e32 v193, 0x7fffffff, v193
	v_and_b32_e32 v192, 0x7fffffff, v192
	v_and_b32_e32 v195, 0x7fffffff, v195
	v_and_b32_e32 v194, 0x7fffffff, v194
	v_and_b32_e32 v201, 0x7fffffff, v201
	v_and_b32_e32 v200, 0x7fffffff, v200
	v_and_b32_e32 v203, 0x7fffffff, v203
	v_and_b32_e32 v202, 0x7fffffff, v202
	v_and_b32_e32 v205, 0x7fffffff, v205
	v_and_b32_e32 v204, 0x7fffffff, v204
	v_and_b32_e32 v207, 0x7fffffff, v207
	v_and_b32_e32 v206, 0x7fffffff, v206
	v_and_b32_e32 v209, 0x7fffffff, v209
	v_and_b32_e32 v208, 0x7fffffff, v208
	v_and_b32_e32 v211, 0x7fffffff, v211
	v_and_b32_e32 v210, 0x7fffffff, v210
	v_and_b32_e32 v215, 0x7fffffff, v215
	v_and_b32_e32 v214, 0x7fffffff, v214
	v_and_b32_e32 v223, 0x7fffffff, v223
	v_and_b32_e32 v222, 0x7fffffff, v222
	v_and_b32_e32 v161, 0x7fffffff, v161
	v_and_b32_e32 v160, 0x7fffffff, v160
	v_and_b32_e32 v228, 0x7fffffff, v128
	v_and_b32_e32 v229, 0x7fffffff, v155
	v_mov_b32_e32 v155, v154
	v_fmac_f32_e32 v94, v154, v214
	v_fmac_f32_e32 v95, v155, v215
	v_fmac_f32_e32 v92, v154, v208
	v_fmac_f32_e32 v93, v155, v209
	v_fmac_f32_e32 v90, v154, v204
	v_fmac_f32_e32 v91, v155, v205
	v_fmac_f32_e32 v88, v154, v200
	v_fmac_f32_e32 v89, v155, v201
	v_fmac_f32_e32 v86, v154, v192
	v_fmac_f32_e32 v87, v155, v193
	v_fmac_f32_e32 v84, v154, v186
	v_fmac_f32_e32 v85, v155, v187
	v_fmac_f32_e32 v82, v154, v160
	v_fmac_f32_e32 v83, v155, v161
	v_fmac_f32_e32 v80, v156, v228
	v_fmac_f32_e32 v81, v157, v229
	v_fmac_f32_e32 v78, v154, v222
	v_fmac_f32_e32 v79, v155, v223
	v_fmac_f32_e32 v76, v154, v210
	v_fmac_f32_e32 v77, v155, v211
	v_fmac_f32_e32 v74, v154, v206
	v_fmac_f32_e32 v75, v155, v207
	v_fmac_f32_e32 v72, v154, v202
	v_fmac_f32_e32 v73, v155, v203
	v_fmac_f32_e32 v70, v154, v194
	v_fmac_f32_e32 v71, v155, v195
	v_fmac_f32_e32 v68, v154, v188
	v_fmac_f32_e32 v69, v155, v189
	v_fmac_f32_e32 v66, v154, v162
	v_fmac_f32_e32 v67, v155, v163
	v_fmac_f32_e32 v64, v156, v158
	v_fmac_f32_e32 v65, v157, v159
	v_fmac_f32_e32 v126, v154, v214
	v_fmac_f32_e32 v127, v155, v215
	v_fmac_f32_e32 v124, v154, v208
	v_fmac_f32_e32 v125, v155, v209
	v_fmac_f32_e32 v122, v154, v204
	v_fmac_f32_e32 v123, v155, v205
	v_fmac_f32_e32 v120, v154, v200
	v_fmac_f32_e32 v121, v155, v201
	v_fmac_f32_e32 v118, v154, v192
	v_fmac_f32_e32 v119, v155, v193
	v_fmac_f32_e32 v116, v154, v186
	v_fmac_f32_e32 v117, v155, v187
	v_fmac_f32_e32 v114, v154, v160
	v_fmac_f32_e32 v115, v155, v161
	v_fmac_f32_e32 v112, v156, v228
	v_fmac_f32_e32 v113, v157, v229
	v_fmac_f32_e32 v110, v154, v222
	v_fmac_f32_e32 v111, v155, v223
	v_fmac_f32_e32 v108, v154, v210
	v_fmac_f32_e32 v109, v155, v211
	v_fmac_f32_e32 v106, v154, v206
	v_fmac_f32_e32 v107, v155, v207
	v_fmac_f32_e32 v104, v154, v202
	v_fmac_f32_e32 v105, v155, v203
	v_fmac_f32_e32 v102, v154, v194
	v_fmac_f32_e32 v103, v155, v195
	v_fmac_f32_e32 v100, v154, v188
	v_fmac_f32_e32 v101, v155, v189
	v_fmac_f32_e32 v98, v154, v162
	v_fmac_f32_e32 v99, v155, v163
	v_fmac_f32_e32 v96, v156, v158
	v_fmac_f32_e32 v97, v157, v159
	s_branch .LBB0_341
